# softmax: packed sub (x-m) and packed row-sum accumulation in A tiles, packed row-sum in C pair tiles
# baseline (speedup 1.0000x reference)
.LBB0_172:
	v_pk_add_f32 v[2:3], v[14:15], v[54:55]
	v_pk_add_f32 v[2:3], v[2:3], v[56:57]
	v_pk_add_f32 v[2:3], v[2:3], v[58:59]
	v_pk_add_f32 v[2:3], v[2:3], v[60:61]
	v_pk_add_f32 v[2:3], v[2:3], v[62:63]
	v_pk_add_f32 v[2:3], v[2:3], v[64:65]
	v_pk_add_f32 v[2:3], v[2:3], v[66:67]
	v_pk_add_f32 v[2:3], v[2:3], v[68:69]
	v_pk_add_f32 v[2:3], v[2:3], v[70:71]
	v_pk_add_f32 v[2:3], v[2:3], v[72:73]
	v_pk_add_f32 v[2:3], v[2:3], v[74:75]
	v_pk_add_f32 v[2:3], v[2:3], v[76:77]
	v_pk_add_f32 v[2:3], v[2:3], v[78:79]
	v_pk_add_f32 v[2:3], v[2:3], v[118:119]
	v_add_f32_e32 v2, v2, v3
	v_add_f32_e32 v2, v53, v2
	v_add_f32_e32 v2, v120, v2
	v_fmac_f32_e32 v2, v117, v0
	v_mov_b32_e32 v117, v2
	s_cmp_gt_i32 s20, s2
	s_cbranch_scc1 .LBB0_163
	s_branch .LBB0_159

.LBB0_748:
	v_mov_b32_e32 v48, v52
	v_pk_add_f32 v[2:3], v[2:3], v[48:49] op_sel_hi:[1,0] neg_lo:[0,1] neg_hi:[0,1]
	v_exp_f32_e32 v53, v2
	v_pk_add_f32 v[4:5], v[4:5], v[48:49] op_sel_hi:[1,0] neg_lo:[0,1] neg_hi:[0,1]
	v_exp_f32_e32 v55, v4
	v_exp_f32_e32 v54, v3
	v_exp_f32_e32 v57, v5
	v_pk_add_f32 v[6:7], v[6:7], v[48:49] op_sel_hi:[1,0] neg_lo:[0,1] neg_hi:[0,1]
	v_exp_f32_e32 v56, v6
	v_pk_add_f32 v[8:9], v[8:9], v[48:49] op_sel_hi:[1,0] neg_lo:[0,1] neg_hi:[0,1]
	v_exp_f32_e32 v59, v8
	v_exp_f32_e32 v58, v7
	v_exp_f32_e32 v61, v9
	v_pk_add_f32 v[10:11], v[10:11], v[48:49] op_sel_hi:[1,0] neg_lo:[0,1] neg_hi:[0,1]
	v_exp_f32_e32 v60, v10
	v_pk_add_f32 v[12:13], v[12:13], v[48:49] op_sel_hi:[1,0] neg_lo:[0,1] neg_hi:[0,1]
	v_exp_f32_e32 v63, v12
	v_exp_f32_e32 v62, v11
	v_exp_f32_e32 v64, v13
	v_sub_f32_e32 v2, v14, v52
	v_exp_f32_e32 v14, v2
	v_pk_add_f32 v[176:177], v[176:177], v[48:49] op_sel_hi:[1,0] neg_lo:[0,1] neg_hi:[0,1]
	v_exp_f32_e32 v65, v176
	v_sub_f32_e32 v2, v15, v52
	v_exp_f32_e32 v15, v2
	v_exp_f32_e32 v67, v177
	v_pk_add_f32 v[178:179], v[178:179], v[48:49] op_sel_hi:[1,0] neg_lo:[0,1] neg_hi:[0,1]
	v_exp_f32_e32 v66, v178
	v_pk_add_f32 v[180:181], v[180:181], v[48:49] op_sel_hi:[1,0] neg_lo:[0,1] neg_hi:[0,1]
	v_exp_f32_e32 v69, v180
	v_exp_f32_e32 v68, v179
	v_exp_f32_e32 v71, v181
	v_pk_add_f32 v[182:183], v[182:183], v[48:49] op_sel_hi:[1,0] neg_lo:[0,1] neg_hi:[0,1]
	v_exp_f32_e32 v70, v182
	v_pk_add_f32 v[184:185], v[184:185], v[48:49] op_sel_hi:[1,0] neg_lo:[0,1] neg_hi:[0,1]
	v_exp_f32_e32 v73, v184
	v_exp_f32_e32 v72, v183
	v_exp_f32_e32 v75, v185
	v_pk_add_f32 v[186:187], v[186:187], v[48:49] op_sel_hi:[1,0] neg_lo:[0,1] neg_hi:[0,1]
	v_exp_f32_e32 v74, v186
	v_pk_add_f32 v[188:189], v[188:189], v[48:49] op_sel_hi:[1,0] neg_lo:[0,1] neg_hi:[0,1]
	v_exp_f32_e32 v77, v188
	v_exp_f32_e32 v76, v187
	v_exp_f32_e32 v79, v189
	v_pk_add_f32 v[190:191], v[190:191], v[48:49] op_sel_hi:[1,0] neg_lo:[0,1] neg_hi:[0,1]
	v_exp_f32_e32 v78, v190
	v_pk_add_f32 v[192:193], v[192:193], v[48:49] op_sel_hi:[1,0] neg_lo:[0,1] neg_hi:[0,1]
	v_exp_f32_e32 v176, v192
	v_exp_f32_e32 v151, v191
	v_exp_f32_e32 v177, v193
	ds_read_b64_tr_b16 v[190:191], v213 offset:0
	ds_read_b64_tr_b16 v[192:193], v213 offset:1536
	ds_read_b64_tr_b16 v[186:187], v213 offset:64
	ds_read_b64_tr_b16 v[188:189], v213 offset:1600
	ds_read_b64_tr_b16 v[182:183], v213 offset:3072
	ds_read_b64_tr_b16 v[184:185], v213 offset:4608
	ds_read_b64_tr_b16 v[178:179], v213 offset:3136
	ds_read_b64_tr_b16 v[180:181], v213 offset:4672
	ds_read_b64_tr_b16 v[48:49], v213 offset:6144
	ds_read_b64_tr_b16 v[50:51], v213 offset:7680
	ds_read_b64_tr_b16 v[10:11], v213 offset:6208
	ds_read_b64_tr_b16 v[12:13], v213 offset:7744
	ds_read_b64_tr_b16 v[6:7], v213 offset:9216
	ds_read_b64_tr_b16 v[8:9], v213 offset:10752
	ds_read_b64_tr_b16 v[2:3], v213 offset:9280
	ds_read_b64_tr_b16 v[4:5], v213 offset:10816
	s_waitcnt lgkmcnt(0)
	v_cvt_pk_bf16_f32 v226, v53, v54
	v_cvt_pk_bf16_f32 v227, v56, v58
	v_cvt_pk_bf16_f32 v228, v60, v62
	v_cvt_pk_bf16_f32 v229, v14, v15
	s_andn2_b64 vcc, exec, s[16:17]
	v_mfma_f32_32x32x16_bf16 v[32:47], v[190:193], v[226:229], v[32:47]
	v_mfma_f32_32x32x16_bf16 v[16:31], v[186:189], v[226:229], v[16:31]
	v_cvt_pk_bf16_f32 v186, v66, v68
	v_cvt_pk_bf16_f32 v187, v70, v72
	v_cvt_pk_bf16_f32 v188, v74, v76
	v_cvt_pk_bf16_f32 v189, v78, v151
	s_nop 0
	v_mfma_f32_32x32x16_bf16 v[32:47], v[182:185], v[186:189], v[32:47]
	v_mfma_f32_32x32x16_bf16 v[16:31], v[178:181], v[186:189], v[16:31]
	s_cbranch_vccnz .LBB0_750
	v_cvt_pk_bf16_f32 v178, v55, v57
	v_cvt_pk_bf16_f32 v179, v59, v61
	v_cvt_pk_bf16_f32 v180, v63, v64
	v_cvt_pk_bf16_f32 v181, v65, v67
	s_nop 0
	v_mfma_f32_32x32x16_bf16 v[32:47], v[48:51], v[178:181], v[32:47]
	v_mfma_f32_32x32x16_bf16 v[16:31], v[10:13], v[178:181], v[16:31]
	v_cvt_pk_bf16_f32 v10, v69, v71
	v_cvt_pk_bf16_f32 v11, v73, v75
	v_cvt_pk_bf16_f32 v12, v77, v79
	v_cvt_pk_bf16_f32 v13, v176, v177
	s_nop 0
	v_mfma_f32_32x32x16_bf16 v[32:47], v[6:9], v[10:13], v[32:47]
	v_mfma_f32_32x32x16_bf16 v[16:31], v[2:5], v[10:13], v[16:31]
.LBB0_750:
	v_pk_add_f32 v[2:3], v[14:15], v[54:55]
	v_pk_add_f32 v[2:3], v[2:3], v[56:57]
	v_pk_add_f32 v[2:3], v[2:3], v[58:59]
	v_pk_add_f32 v[2:3], v[2:3], v[60:61]
	v_pk_add_f32 v[2:3], v[2:3], v[62:63]
	v_pk_add_f32 v[2:3], v[2:3], v[64:65]
	v_pk_add_f32 v[2:3], v[2:3], v[66:67]
	v_pk_add_f32 v[2:3], v[2:3], v[68:69]
	v_pk_add_f32 v[2:3], v[2:3], v[70:71]
	v_pk_add_f32 v[2:3], v[2:3], v[72:73]
	v_pk_add_f32 v[2:3], v[2:3], v[74:75]
	v_pk_add_f32 v[2:3], v[2:3], v[76:77]
	v_pk_add_f32 v[2:3], v[2:3], v[78:79]
	v_pk_add_f32 v[2:3], v[2:3], v[176:177]
	v_add_f32_e32 v2, v2, v3
	v_add_f32_e32 v2, v53, v2
	v_add_f32_e32 v2, v151, v2
	v_fmac_f32_e32 v2, v224, v0
	v_mov_b32_e32 v224, v2
	v_mov_b32_e32 v225, v52

.LBB0_787:
	v_mov_b32_e32 v48, v52
	v_pk_add_f32 v[2:3], v[2:3], v[48:49] op_sel_hi:[1,0] neg_lo:[0,1] neg_hi:[0,1]
	v_exp_f32_e32 v53, v2
	v_pk_add_f32 v[4:5], v[4:5], v[48:49] op_sel_hi:[1,0] neg_lo:[0,1] neg_hi:[0,1]
	v_exp_f32_e32 v55, v4
	v_exp_f32_e32 v54, v3
	v_exp_f32_e32 v57, v5
	v_pk_add_f32 v[6:7], v[6:7], v[48:49] op_sel_hi:[1,0] neg_lo:[0,1] neg_hi:[0,1]
	v_exp_f32_e32 v56, v6
	v_pk_add_f32 v[8:9], v[8:9], v[48:49] op_sel_hi:[1,0] neg_lo:[0,1] neg_hi:[0,1]
	v_exp_f32_e32 v59, v8
	v_exp_f32_e32 v58, v7
	v_exp_f32_e32 v61, v9
	v_pk_add_f32 v[10:11], v[10:11], v[48:49] op_sel_hi:[1,0] neg_lo:[0,1] neg_hi:[0,1]
	v_exp_f32_e32 v60, v10
	v_pk_add_f32 v[12:13], v[12:13], v[48:49] op_sel_hi:[1,0] neg_lo:[0,1] neg_hi:[0,1]
	v_exp_f32_e32 v63, v12
	v_exp_f32_e32 v62, v11
	v_exp_f32_e32 v64, v13
	v_sub_f32_e32 v2, v14, v52
	v_exp_f32_e32 v14, v2
	v_pk_add_f32 v[176:177], v[176:177], v[48:49] op_sel_hi:[1,0] neg_lo:[0,1] neg_hi:[0,1]
	v_exp_f32_e32 v65, v176
	v_sub_f32_e32 v2, v15, v52
	v_exp_f32_e32 v15, v2
	v_exp_f32_e32 v67, v177
	v_pk_add_f32 v[178:179], v[178:179], v[48:49] op_sel_hi:[1,0] neg_lo:[0,1] neg_hi:[0,1]
	v_exp_f32_e32 v66, v178
	v_pk_add_f32 v[180:181], v[180:181], v[48:49] op_sel_hi:[1,0] neg_lo:[0,1] neg_hi:[0,1]
	v_exp_f32_e32 v69, v180
	v_exp_f32_e32 v68, v179
	v_exp_f32_e32 v71, v181
	v_pk_add_f32 v[182:183], v[182:183], v[48:49] op_sel_hi:[1,0] neg_lo:[0,1] neg_hi:[0,1]
	v_exp_f32_e32 v70, v182
	v_pk_add_f32 v[184:185], v[184:185], v[48:49] op_sel_hi:[1,0] neg_lo:[0,1] neg_hi:[0,1]
	v_exp_f32_e32 v73, v184
	v_exp_f32_e32 v72, v183
	v_exp_f32_e32 v75, v185
	v_pk_add_f32 v[186:187], v[186:187], v[48:49] op_sel_hi:[1,0] neg_lo:[0,1] neg_hi:[0,1]
	v_exp_f32_e32 v74, v186
	v_pk_add_f32 v[188:189], v[188:189], v[48:49] op_sel_hi:[1,0] neg_lo:[0,1] neg_hi:[0,1]
	v_exp_f32_e32 v77, v188
	v_exp_f32_e32 v76, v187
	v_exp_f32_e32 v79, v189
	v_pk_add_f32 v[190:191], v[190:191], v[48:49] op_sel_hi:[1,0] neg_lo:[0,1] neg_hi:[0,1]
	v_exp_f32_e32 v78, v190
	v_pk_add_f32 v[192:193], v[192:193], v[48:49] op_sel_hi:[1,0] neg_lo:[0,1] neg_hi:[0,1]
	v_exp_f32_e32 v176, v192
	v_exp_f32_e32 v151, v191
	v_exp_f32_e32 v177, v193
	v_add_u32_e32 v225, s23, v205
	ds_read_b64_tr_b16 v[190:191], v225 offset:0
	ds_read_b64_tr_b16 v[192:193], v225 offset:1536
	ds_read_b64_tr_b16 v[186:187], v225 offset:64
	ds_read_b64_tr_b16 v[188:189], v225 offset:1600
	ds_read_b64_tr_b16 v[182:183], v225 offset:3072
	ds_read_b64_tr_b16 v[184:185], v225 offset:4608
	ds_read_b64_tr_b16 v[178:179], v225 offset:3136
	ds_read_b64_tr_b16 v[180:181], v225 offset:4672
	ds_read_b64_tr_b16 v[48:49], v225 offset:6144
	ds_read_b64_tr_b16 v[50:51], v225 offset:7680
	ds_read_b64_tr_b16 v[10:11], v225 offset:6208
	ds_read_b64_tr_b16 v[12:13], v225 offset:7744
	ds_read_b64_tr_b16 v[6:7], v225 offset:9216
	ds_read_b64_tr_b16 v[8:9], v225 offset:10752
	ds_read_b64_tr_b16 v[2:3], v225 offset:9280
	ds_read_b64_tr_b16 v[4:5], v225 offset:10816
	s_waitcnt lgkmcnt(0)
	v_cvt_pk_bf16_f32 v228, v53, v54
	v_cvt_pk_bf16_f32 v229, v56, v58
	v_cvt_pk_bf16_f32 v230, v60, v62
	v_cvt_pk_bf16_f32 v231, v14, v15
	s_andn2_b64 vcc, exec, s[16:17]
	v_mfma_f32_32x32x16_bf16 v[32:47], v[190:193], v[228:231], v[32:47]
	v_mfma_f32_32x32x16_bf16 v[16:31], v[186:189], v[228:231], v[16:31]
	v_cvt_pk_bf16_f32 v186, v66, v68
	v_cvt_pk_bf16_f32 v187, v70, v72
	v_cvt_pk_bf16_f32 v188, v74, v76
	v_cvt_pk_bf16_f32 v189, v78, v151
	s_nop 0
	v_mfma_f32_32x32x16_bf16 v[32:47], v[182:185], v[186:189], v[32:47]
	v_mfma_f32_32x32x16_bf16 v[16:31], v[178:181], v[186:189], v[16:31]
	s_cbranch_vccnz .LBB0_789
	v_cvt_pk_bf16_f32 v178, v55, v57
	v_cvt_pk_bf16_f32 v179, v59, v61
	v_cvt_pk_bf16_f32 v180, v63, v64
	v_cvt_pk_bf16_f32 v181, v65, v67
	s_nop 0
	v_mfma_f32_32x32x16_bf16 v[32:47], v[48:51], v[178:181], v[32:47]
	v_mfma_f32_32x32x16_bf16 v[16:31], v[10:13], v[178:181], v[16:31]
	v_cvt_pk_bf16_f32 v10, v69, v71
	v_cvt_pk_bf16_f32 v11, v73, v75
	v_cvt_pk_bf16_f32 v12, v77, v79
	v_cvt_pk_bf16_f32 v13, v176, v177
	s_nop 0
	v_mfma_f32_32x32x16_bf16 v[32:47], v[6:9], v[10:13], v[32:47]
	v_mfma_f32_32x32x16_bf16 v[16:31], v[2:5], v[10:13], v[16:31]

.LBB0_800:
	v_mov_b32_e32 v48, v52
	v_pk_add_f32 v[2:3], v[2:3], v[48:49] op_sel_hi:[1,0] neg_lo:[0,1] neg_hi:[0,1]
	v_exp_f32_e32 v53, v2
	v_pk_add_f32 v[4:5], v[4:5], v[48:49] op_sel_hi:[1,0] neg_lo:[0,1] neg_hi:[0,1]
	v_exp_f32_e32 v55, v4
	v_exp_f32_e32 v54, v3
	v_exp_f32_e32 v57, v5
	v_pk_add_f32 v[6:7], v[6:7], v[48:49] op_sel_hi:[1,0] neg_lo:[0,1] neg_hi:[0,1]
	v_exp_f32_e32 v56, v6
	v_pk_add_f32 v[8:9], v[8:9], v[48:49] op_sel_hi:[1,0] neg_lo:[0,1] neg_hi:[0,1]
	v_exp_f32_e32 v59, v8
	v_exp_f32_e32 v58, v7
	v_exp_f32_e32 v61, v9
	v_pk_add_f32 v[10:11], v[10:11], v[48:49] op_sel_hi:[1,0] neg_lo:[0,1] neg_hi:[0,1]
	v_exp_f32_e32 v60, v10
	v_pk_add_f32 v[12:13], v[12:13], v[48:49] op_sel_hi:[1,0] neg_lo:[0,1] neg_hi:[0,1]
	v_exp_f32_e32 v63, v12
	v_exp_f32_e32 v62, v11
	v_exp_f32_e32 v64, v13
	v_sub_f32_e32 v2, v14, v52
	v_exp_f32_e32 v14, v2
	v_pk_add_f32 v[176:177], v[176:177], v[48:49] op_sel_hi:[1,0] neg_lo:[0,1] neg_hi:[0,1]
	v_exp_f32_e32 v65, v176
	v_sub_f32_e32 v2, v15, v52
	v_exp_f32_e32 v15, v2
	v_exp_f32_e32 v67, v177
	v_pk_add_f32 v[178:179], v[178:179], v[48:49] op_sel_hi:[1,0] neg_lo:[0,1] neg_hi:[0,1]
	v_exp_f32_e32 v66, v178
	v_pk_add_f32 v[180:181], v[180:181], v[48:49] op_sel_hi:[1,0] neg_lo:[0,1] neg_hi:[0,1]
	v_exp_f32_e32 v69, v180
	v_exp_f32_e32 v68, v179
	v_exp_f32_e32 v71, v181
	v_pk_add_f32 v[182:183], v[182:183], v[48:49] op_sel_hi:[1,0] neg_lo:[0,1] neg_hi:[0,1]
	v_exp_f32_e32 v70, v182
	v_pk_add_f32 v[184:185], v[184:185], v[48:49] op_sel_hi:[1,0] neg_lo:[0,1] neg_hi:[0,1]
	v_exp_f32_e32 v73, v184
	v_exp_f32_e32 v72, v183
	v_exp_f32_e32 v75, v185
	v_pk_add_f32 v[186:187], v[186:187], v[48:49] op_sel_hi:[1,0] neg_lo:[0,1] neg_hi:[0,1]
	v_exp_f32_e32 v74, v186
	v_pk_add_f32 v[188:189], v[188:189], v[48:49] op_sel_hi:[1,0] neg_lo:[0,1] neg_hi:[0,1]
	v_exp_f32_e32 v77, v188
	v_exp_f32_e32 v76, v187
	v_exp_f32_e32 v79, v189
	v_pk_add_f32 v[190:191], v[190:191], v[48:49] op_sel_hi:[1,0] neg_lo:[0,1] neg_hi:[0,1]
	v_exp_f32_e32 v78, v190
	v_pk_add_f32 v[192:193], v[192:193], v[48:49] op_sel_hi:[1,0] neg_lo:[0,1] neg_hi:[0,1]
	v_exp_f32_e32 v176, v192
	v_exp_f32_e32 v151, v191
	v_exp_f32_e32 v177, v193
	v_add_u32_e32 v225, s21, v205
	ds_read_b64_tr_b16 v[190:191], v225 offset:0
	ds_read_b64_tr_b16 v[192:193], v225 offset:1536
	ds_read_b64_tr_b16 v[186:187], v225 offset:64
	ds_read_b64_tr_b16 v[188:189], v225 offset:1600
	ds_read_b64_tr_b16 v[182:183], v225 offset:3072
	ds_read_b64_tr_b16 v[184:185], v225 offset:4608
	ds_read_b64_tr_b16 v[178:179], v225 offset:3136
	ds_read_b64_tr_b16 v[180:181], v225 offset:4672
	ds_read_b64_tr_b16 v[48:49], v225 offset:6144
	ds_read_b64_tr_b16 v[50:51], v225 offset:7680
	ds_read_b64_tr_b16 v[10:11], v225 offset:6208
	ds_read_b64_tr_b16 v[12:13], v225 offset:7744
	ds_read_b64_tr_b16 v[6:7], v225 offset:9216
	ds_read_b64_tr_b16 v[8:9], v225 offset:10752
	ds_read_b64_tr_b16 v[2:3], v225 offset:9280
	ds_read_b64_tr_b16 v[4:5], v225 offset:10816
	s_waitcnt lgkmcnt(0)
	v_cvt_pk_bf16_f32 v228, v53, v54
	v_cvt_pk_bf16_f32 v229, v56, v58
	v_cvt_pk_bf16_f32 v230, v60, v62
	v_cvt_pk_bf16_f32 v231, v14, v15
	s_andn2_b64 vcc, exec, s[16:17]
	v_mfma_f32_32x32x16_bf16 v[32:47], v[190:193], v[228:231], v[32:47]
	v_mfma_f32_32x32x16_bf16 v[16:31], v[186:189], v[228:231], v[16:31]
	v_cvt_pk_bf16_f32 v186, v66, v68
	v_cvt_pk_bf16_f32 v187, v70, v72
	v_cvt_pk_bf16_f32 v188, v74, v76
	v_cvt_pk_bf16_f32 v189, v78, v151
	s_nop 0
	v_mfma_f32_32x32x16_bf16 v[32:47], v[182:185], v[186:189], v[32:47]
	v_mfma_f32_32x32x16_bf16 v[16:31], v[178:181], v[186:189], v[16:31]
	s_cbranch_vccnz .LBB0_802
	v_cvt_pk_bf16_f32 v178, v55, v57
	v_cvt_pk_bf16_f32 v179, v59, v61
	v_cvt_pk_bf16_f32 v180, v63, v64
	v_cvt_pk_bf16_f32 v181, v65, v67
	s_nop 0
	v_mfma_f32_32x32x16_bf16 v[32:47], v[48:51], v[178:181], v[32:47]
	v_mfma_f32_32x32x16_bf16 v[16:31], v[10:13], v[178:181], v[16:31]
	v_cvt_pk_bf16_f32 v10, v69, v71
	v_cvt_pk_bf16_f32 v11, v73, v75
	v_cvt_pk_bf16_f32 v12, v77, v79
	v_cvt_pk_bf16_f32 v13, v176, v177
	s_nop 0
	v_mfma_f32_32x32x16_bf16 v[32:47], v[6:9], v[10:13], v[32:47]
	v_mfma_f32_32x32x16_bf16 v[16:31], v[2:5], v[10:13], v[16:31]
